# final-norm phase: the four f32 output stores of its main loop carry the non-temporal (nt) cache hint (write-once output)
# speedup vs baseline: 1.0038x; 1.0020x over previous
; __device__ __forceinline__ float bflo(unsigned x) { return __uint_as_float(x << 16); }
; __device__ __forceinline__ float bfhi(unsigned x) { return __uint_as_float(x & 0xffff0000u); }
; __device__ __forceinline__ void ph_final(const bf16* X3, float* Y, const float* w, int vcu, int G, int tid, const bf16* fslab, int fS, const float* fgate, float fsc) {
;     ...
;     for (int row = gw; row < MT; row += NGW) {
;         f32x4 v[4]; float s = 0.f;
; #pragma unroll
;         for (int j = 0; j < 4; ++j) v[j] = vn[j];
;         if (row + NGW < MT) load_row4(X3, true, (size_t)(row + NGW), lane, vn);
;         if (row >= MP) { const int mb = 8 + ((row - MP) >> 6);
;             f32x4 a[4];
; #pragma unroll
;             for (int j = 0; j < 4; ++j) a[j] = (f32x4){0.f, 0.f, 0.f, 0.f};
;             for (int ks = 0; ks < fS; ++ks) { const v2u* sp = (const v2u*)(fslab + ((size_t)ks * MS + (row - MP)) * DM);
; #pragma unroll
;                 for (int j = 0; j < 4; ++j) { const v2u r = sp[lane + 64 * j]; a[j] += (f32x4){bflo(r.x), bfhi(r.x), bflo(r.y), bfhi(r.y)}; } }
; #pragma unroll
;             for (int j = 0; j < 4; ++j) v[j] += ((const f32x4*)(fgate + (size_t)mb * 9216))[lane + 64 * j] * fsc * a[j];
;         }
; #pragma unroll
;         for (int j = 0; j < 4; ++j) s += (v[j][0] * v[j][0] + v[j][1] * v[j][1]) + (v[j][2] * v[j][2] + v[j][3] * v[j][3]);
;         const float rstd = rsqrtf(wave_sum(s) * (1.0f / DM) + EPSN);
;         f32x4* yr = (f32x4*)(Y + (size_t)row * DM);
; #pragma unroll
;         for (int j = 0; j < 4; ++j) yr[lane + 64 * j] = v[j] * rstd * wv[j];
.LBB0_1595:
	v_pk_mul_f32 v[42:43], v[36:37], v[36:37]
	v_pk_mul_f32 v[44:45], v[34:35], v[34:35]
	v_pk_mul_f32 v[38:39], v[32:33], v[32:33]
	v_pk_mul_f32 v[40:41], v[30:31], v[30:31]
	v_pk_mov_b32 v[46:47], v[44:45], v[42:43] op_sel:[1,0]
	v_mov_b32_e32 v45, v43
	v_pk_add_f32 v[42:43], v[46:47], v[44:45]
	v_pk_mov_b32 v[44:45], v[40:41], v[38:39] op_sel:[1,0]
	v_mov_b32_e32 v41, v39
	v_pk_add_f32 v[38:39], v[44:45], v[40:41]
	v_pk_add_f32 v[42:43], v[42:43], v[42:43] op_sel_hi:[0,1]
	v_pk_add_f32 v[38:39], v[38:39], v[38:39] op_sel_hi:[0,1]
	v_mul_f32_e32 v38, v26, v26
	v_pk_fma_f32 v[40:41], v[26:27], v[26:27], v[38:39] op_sel_hi:[1,1,0]
	v_mul_f32_e32 v38, v28, v28
	v_pk_fma_f32 v[44:45], v[28:29], v[28:29], v[38:39] op_sel_hi:[1,1,0]
	v_mul_f32_e32 v40, v20, v20
	v_mul_f32_e32 v44, v21, v21
	v_mul_f32_e32 v42, v22, v22
	v_mul_f32_e32 v38, v23, v23
	v_pk_add_f32 v[40:41], v[40:41], v[44:45]
	v_pk_add_f32 v[38:39], v[42:43], v[38:39]
	v_lshl_add_u64 v[24:25], v[24:25], 0, s[6:7]
	v_pk_add_f32 v[38:39], v[40:41], v[38:39]
	s_mov_b32 s2, s9
	v_add_f32_e32 v38, v38, v39
	ds_bpermute_b32 v39, v80, v38
	s_waitcnt lgkmcnt(0)
	v_add_f32_e32 v38, v38, v39
	ds_bpermute_b32 v39, v81, v38
	s_waitcnt lgkmcnt(0)
	v_add_f32_e32 v38, v38, v39
	ds_bpermute_b32 v39, v82, v38
	s_waitcnt lgkmcnt(0)
	v_add_f32_e32 v38, v38, v39
	ds_bpermute_b32 v39, v83, v38
	s_waitcnt lgkmcnt(0)
	v_add_f32_e32 v38, v38, v39
	ds_bpermute_b32 v39, v84, v38
	s_waitcnt lgkmcnt(0)
	v_add_f32_e32 v38, v38, v39
	ds_bpermute_b32 v39, v85, v38
	s_waitcnt lgkmcnt(0)
	v_add_f32_e32 v38, v38, v39
	v_fmamk_f32 v38, v38, 0x3a800000, v90
	v_mul_f32_e32 v39, 0x4b800000, v38
	v_cmp_gt_f32_e32 vcc, s1, v38
	s_nop 1
	v_cndmask_b32_e32 v38, v38, v39, vcc
	v_rsq_f32_e32 v38, v38
	s_nop 0
	v_mul_f32_e32 v39, 0x45800000, v38
	v_cndmask_b32_e32 v38, v38, v39, vcc
	v_pk_mul_f32 v[34:35], v[34:35], v[38:39] op_sel_hi:[1,0]
	v_pk_mul_f32 v[36:37], v[36:37], v[38:39] op_sel_hi:[1,0]
	v_pk_mul_f32 v[32:33], v[32:33], v[38:39] op_sel_hi:[1,0]
	v_pk_mul_f32 v[30:31], v[30:31], v[38:39] op_sel_hi:[1,0]
	v_pk_mul_f32 v[40:41], v[26:27], v[38:39] op_sel_hi:[1,0]
	v_pk_mul_f32 v[42:43], v[28:29], v[38:39] op_sel_hi:[1,0]
	v_pk_mul_f32 v[28:29], v[2:3], v[36:37]
	v_pk_mul_f32 v[26:27], v[0:1], v[34:35]
	v_pk_mul_f32 v[32:33], v[6:7], v[32:33]
	v_pk_mul_f32 v[20:21], v[20:21], v[38:39] op_sel_hi:[1,0]
	v_pk_mul_f32 v[22:23], v[22:23], v[38:39] op_sel_hi:[1,0]
	v_pk_mul_f32 v[30:31], v[4:5], v[30:31]
	v_pk_mul_f32 v[34:35], v[10:11], v[42:43]
	global_store_dwordx4 v[18:19], v[26:29], off offset:-3072 nt
	global_store_dwordx4 v[18:19], v[30:33], off offset:-2048 nt
	v_pk_mul_f32 v[22:23], v[14:15], v[22:23]
	v_pk_mul_f32 v[20:21], v[12:13], v[20:21]
	v_pk_mul_f32 v[32:33], v[8:9], v[40:41]
	global_store_dwordx4 v[18:19], v[32:35], off offset:-1024 nt
	global_store_dwordx4 v[18:19], v[20:23], off nt
	v_lshl_add_u64 v[18:19], v[18:19], 0, s[4:5]
	s_andn2_b64 vcc, exec, s[10:11]
	v_mov_b32_e32 v20, v104
	v_mov_b32_e32 v21, v105
	v_mov_b32_e32 v22, v106
	v_mov_b32_e32 v23, v107
	v_mov_b32_e32 v26, v100
	v_mov_b32_e32 v27, v101
	v_mov_b32_e32 v28, v102
	v_mov_b32_e32 v29, v103
	v_mov_b32_e32 v30, v96
	v_mov_b32_e32 v31, v97
	v_mov_b32_e32 v32, v98
	v_mov_b32_e32 v33, v99
	v_mov_b32_e32 v34, v92
	v_mov_b32_e32 v35, v93
	v_mov_b32_e32 v36, v94
	v_mov_b32_e32 v37, v95
	s_cbranch_vccz .LBB0_1600
